# diff: cross-half max exchange only inside the rare rescale path (trigger is a wave-level any over the per-lane maxima)
# speedup vs baseline: 1.0168x; 1.0000x over previous
; __device__ __forceinline__ void diff_unit(const Frame& F, int b, int h, int qi, float lam, int dry) {
;     ...
;             float mx = fmaxf(s0[0], s1[0]);
; #pragma unroll
;             for (int r = 1; r < 16; ++r) mx = fmaxf(mx, fmaxf(s0[r], s1[r]));
;             mx = fmaxf(mx, __shfl_xor(mx, 32));
;             const float mxs = mx * LOG2E;
;             if (__any(mxs > ms + 8.0f)) {
;                 const float msn = fmaxf(ms, mxs); const float f = __builtin_amdgcn_exp2f(ms - msn); lsum *= f; ms = msn;
; #pragma unroll
;                 for (int dt = 0; dt < 4; ++dt)
; #pragma unroll
;                     for (int r = 0; r < 16; ++r) O[dt][r] *= f;
;             }
.LBB0_303:
	v_max3_f32 v223, v80, v81, v82
	v_max3_f32 v223, v223, v83, v84
	v_max3_f32 v223, v223, v85, v86
	v_max3_f32 v223, v223, v87, v88
	v_max3_f32 v223, v223, v89, v90
	v_max3_f32 v223, v223, v91, v92
	v_max3_f32 v223, v223, v93, v94
	s_nop 2
	v_max3_f32 v224, v64, v65, v66
	v_max3_f32 v224, v224, v67, v68
	v_max3_f32 v224, v224, v69, v70
	v_max3_f32 v224, v224, v71, v72
	v_max3_f32 v224, v224, v73, v74
	v_max3_f32 v224, v224, v75, v76
	v_max3_f32 v224, v224, v77, v78
	v_max3_f32 v223, v223, v224, v95
	v_max_f32_e32 v223, v223, v79
	v_cmp_lt_f32_e32 vcc, 0x41000000, v223
	s_cbranch_vccz .LBB0_305
	v_mov_b32_e32 v224, v223
	s_nop 1
	v_permlane32_swap_b32_e32 v223, v224
	v_max_f32_e32 v223, v223, v224
	v_max_f32_e32 v223, 0, v223
	v_exp_f32_e64 v224, -v223
	v_add_f32_e32 v185, v185, v223
	v_pk_mul_f32 v[62:63], v[62:63], v[224:225] op_sel_hi:[1,0]
	v_pk_mul_f32 v[60:61], v[60:61], v[224:225] op_sel_hi:[1,0]
	v_pk_mul_f32 v[58:59], v[58:59], v[224:225] op_sel_hi:[1,0]
	v_pk_mul_f32 v[56:57], v[56:57], v[224:225] op_sel_hi:[1,0]
	v_pk_mul_f32 v[54:55], v[54:55], v[224:225] op_sel_hi:[1,0]
	v_pk_mul_f32 v[52:53], v[52:53], v[224:225] op_sel_hi:[1,0]
	v_pk_mul_f32 v[50:51], v[50:51], v[224:225] op_sel_hi:[1,0]
	v_pk_mul_f32 v[48:49], v[48:49], v[224:225] op_sel_hi:[1,0]
	v_pk_mul_f32 v[46:47], v[46:47], v[224:225] op_sel_hi:[1,0]
	v_pk_mul_f32 v[44:45], v[44:45], v[224:225] op_sel_hi:[1,0]
	v_pk_mul_f32 v[42:43], v[42:43], v[224:225] op_sel_hi:[1,0]
	v_pk_mul_f32 v[40:41], v[40:41], v[224:225] op_sel_hi:[1,0]
	v_pk_mul_f32 v[38:39], v[38:39], v[224:225] op_sel_hi:[1,0]
	v_pk_mul_f32 v[36:37], v[36:37], v[224:225] op_sel_hi:[1,0]
	v_pk_mul_f32 v[34:35], v[34:35], v[224:225] op_sel_hi:[1,0]
	v_pk_mul_f32 v[32:33], v[32:33], v[224:225] op_sel_hi:[1,0]
	v_pk_mul_f32 v[30:31], v[30:31], v[224:225] op_sel_hi:[1,0]
	v_pk_mul_f32 v[28:29], v[28:29], v[224:225] op_sel_hi:[1,0]
	v_pk_mul_f32 v[26:27], v[26:27], v[224:225] op_sel_hi:[1,0]
	v_pk_mul_f32 v[24:25], v[24:25], v[224:225] op_sel_hi:[1,0]
	v_pk_mul_f32 v[22:23], v[22:23], v[224:225] op_sel_hi:[1,0]
	v_pk_mul_f32 v[20:21], v[20:21], v[224:225] op_sel_hi:[1,0]
	v_pk_mul_f32 v[18:19], v[18:19], v[224:225] op_sel_hi:[1,0]
	v_pk_mul_f32 v[16:17], v[16:17], v[224:225] op_sel_hi:[1,0]
	v_pk_mul_f32 v[14:15], v[14:15], v[224:225] op_sel_hi:[1,0]
	v_pk_mul_f32 v[12:13], v[12:13], v[224:225] op_sel_hi:[1,0]
	v_pk_mul_f32 v[10:11], v[10:11], v[224:225] op_sel_hi:[1,0]
	v_pk_mul_f32 v[8:9], v[8:9], v[224:225] op_sel_hi:[1,0]
	v_pk_mul_f32 v[6:7], v[6:7], v[224:225] op_sel_hi:[1,0]
	v_pk_mul_f32 v[4:5], v[4:5], v[224:225] op_sel_hi:[1,0]
	v_pk_mul_f32 v[2:3], v[2:3], v[224:225] op_sel_hi:[1,0]
	v_pk_mul_f32 v[0:1], v[0:1], v[224:225] op_sel_hi:[1,0]
	v_mul_f32_e32 v158, v158, v224
	v_sub_f32_e32 v64, v64, v223
	v_sub_f32_e32 v65, v65, v223
	v_sub_f32_e32 v66, v66, v223
	v_sub_f32_e32 v67, v67, v223
	v_sub_f32_e32 v68, v68, v223
	v_sub_f32_e32 v69, v69, v223
	v_sub_f32_e32 v70, v70, v223
	v_sub_f32_e32 v71, v71, v223
	v_sub_f32_e32 v72, v72, v223
	v_sub_f32_e32 v73, v73, v223
	v_sub_f32_e32 v74, v74, v223
	v_sub_f32_e32 v75, v75, v223
	v_sub_f32_e32 v76, v76, v223
	v_sub_f32_e32 v77, v77, v223
	v_sub_f32_e32 v78, v78, v223
	v_sub_f32_e32 v79, v79, v223
	v_sub_f32_e32 v80, v80, v223
	v_sub_f32_e32 v81, v81, v223
	v_sub_f32_e32 v82, v82, v223
	v_sub_f32_e32 v83, v83, v223
	v_sub_f32_e32 v84, v84, v223
	v_sub_f32_e32 v85, v85, v223
	v_sub_f32_e32 v86, v86, v223
	v_sub_f32_e32 v87, v87, v223
	v_sub_f32_e32 v88, v88, v223
	v_sub_f32_e32 v89, v89, v223
	v_sub_f32_e32 v90, v90, v223
	v_sub_f32_e32 v91, v91, v223
	v_sub_f32_e32 v92, v92, v223
	v_sub_f32_e32 v93, v93, v223
	v_sub_f32_e32 v94, v94, v223
	v_sub_f32_e32 v95, v95, v223
	v_sub_f32_e32 v238, v238, v223
	v_sub_f32_e32 v239, v239, v223
	v_sub_f32_e32 v240, v240, v223
	v_sub_f32_e32 v241, v241, v223
	v_sub_f32_e32 v242, v242, v223
	v_sub_f32_e32 v243, v243, v223
	v_sub_f32_e32 v244, v244, v223
	v_sub_f32_e32 v245, v245, v223
	v_sub_f32_e32 v246, v246, v223
	v_sub_f32_e32 v247, v247, v223
	v_sub_f32_e32 v248, v248, v223
	v_sub_f32_e32 v249, v249, v223
	v_sub_f32_e32 v250, v250, v223
	v_sub_f32_e32 v251, v251, v223
	v_sub_f32_e32 v252, v252, v223
	v_sub_f32_e32 v253, v253, v223

; __device__ __forceinline__ void diff_unit(const Frame& F, int b, int h, int qi, float lam, int dry) {
;     ...
;             float mx = fmaxf(s0[0], s1[0]);
; #pragma unroll
;             for (int r = 1; r < 16; ++r) mx = fmaxf(mx, fmaxf(s0[r], s1[r]));
;             mx = fmaxf(mx, __shfl_xor(mx, 32));
;             const float mxs = mx * LOG2E;
;             if (__any(mxs > ms + 8.0f)) {
;                 const float msn = fmaxf(ms, mxs); const float f = __builtin_amdgcn_exp2f(ms - msn); lsum *= f; ms = msn;
; #pragma unroll
;                 for (int dt = 0; dt < 4; ++dt)
; #pragma unroll
;                     for (int r = 0; r < 16; ++r) O[dt][r] *= f;
;             }
.LBB0_322:
	v_max3_f32 v189, v80, v81, v82
	v_max3_f32 v189, v189, v83, v84
	v_max3_f32 v189, v189, v85, v86
	v_max3_f32 v189, v189, v87, v88
	v_max3_f32 v189, v189, v89, v90
	v_max3_f32 v189, v189, v91, v92
	v_max3_f32 v189, v189, v93, v94
	s_nop 2
	v_max3_f32 v190, v64, v65, v66
	v_max3_f32 v190, v190, v67, v68
	v_max3_f32 v190, v190, v69, v70
	v_max3_f32 v190, v190, v71, v72
	v_max3_f32 v190, v190, v73, v74
	v_max3_f32 v190, v190, v75, v76
	v_max3_f32 v190, v190, v77, v78
	v_max3_f32 v189, v189, v190, v95
	v_max_f32_e32 v189, v189, v79
	v_cmp_lt_f32_e32 vcc, 0x41000000, v189
	s_cbranch_vccz .LBB0_324
	v_mov_b32_e32 v190, v189
	s_nop 1
	v_permlane32_swap_b32_e32 v189, v190
	v_max_f32_e32 v189, v189, v190
	v_max_f32_e32 v189, 0, v189
	v_exp_f32_e64 v190, -v189
	v_add_f32_e32 v158, v158, v189
	v_pk_mul_f32 v[62:63], v[62:63], v[190:191] op_sel_hi:[1,0]
	v_pk_mul_f32 v[60:61], v[60:61], v[190:191] op_sel_hi:[1,0]
	v_pk_mul_f32 v[58:59], v[58:59], v[190:191] op_sel_hi:[1,0]
	v_pk_mul_f32 v[56:57], v[56:57], v[190:191] op_sel_hi:[1,0]
	v_pk_mul_f32 v[54:55], v[54:55], v[190:191] op_sel_hi:[1,0]
	v_pk_mul_f32 v[52:53], v[52:53], v[190:191] op_sel_hi:[1,0]
	v_pk_mul_f32 v[50:51], v[50:51], v[190:191] op_sel_hi:[1,0]
	v_pk_mul_f32 v[48:49], v[48:49], v[190:191] op_sel_hi:[1,0]
	v_pk_mul_f32 v[46:47], v[46:47], v[190:191] op_sel_hi:[1,0]
	v_pk_mul_f32 v[44:45], v[44:45], v[190:191] op_sel_hi:[1,0]
	v_pk_mul_f32 v[42:43], v[42:43], v[190:191] op_sel_hi:[1,0]
	v_pk_mul_f32 v[40:41], v[40:41], v[190:191] op_sel_hi:[1,0]
	v_pk_mul_f32 v[38:39], v[38:39], v[190:191] op_sel_hi:[1,0]
	v_pk_mul_f32 v[36:37], v[36:37], v[190:191] op_sel_hi:[1,0]
	v_pk_mul_f32 v[34:35], v[34:35], v[190:191] op_sel_hi:[1,0]
	v_pk_mul_f32 v[32:33], v[32:33], v[190:191] op_sel_hi:[1,0]
	v_pk_mul_f32 v[30:31], v[30:31], v[190:191] op_sel_hi:[1,0]
	v_pk_mul_f32 v[28:29], v[28:29], v[190:191] op_sel_hi:[1,0]
	v_pk_mul_f32 v[26:27], v[26:27], v[190:191] op_sel_hi:[1,0]
	v_pk_mul_f32 v[24:25], v[24:25], v[190:191] op_sel_hi:[1,0]
	v_pk_mul_f32 v[22:23], v[22:23], v[190:191] op_sel_hi:[1,0]
	v_pk_mul_f32 v[20:21], v[20:21], v[190:191] op_sel_hi:[1,0]
	v_pk_mul_f32 v[18:19], v[18:19], v[190:191] op_sel_hi:[1,0]
	v_pk_mul_f32 v[16:17], v[16:17], v[190:191] op_sel_hi:[1,0]
	v_pk_mul_f32 v[14:15], v[14:15], v[190:191] op_sel_hi:[1,0]
	v_pk_mul_f32 v[12:13], v[12:13], v[190:191] op_sel_hi:[1,0]
	v_pk_mul_f32 v[10:11], v[10:11], v[190:191] op_sel_hi:[1,0]
	v_pk_mul_f32 v[8:9], v[8:9], v[190:191] op_sel_hi:[1,0]
	v_pk_mul_f32 v[6:7], v[6:7], v[190:191] op_sel_hi:[1,0]
	v_pk_mul_f32 v[4:5], v[4:5], v[190:191] op_sel_hi:[1,0]
	v_pk_mul_f32 v[2:3], v[2:3], v[190:191] op_sel_hi:[1,0]
	v_pk_mul_f32 v[0:1], v[0:1], v[190:191] op_sel_hi:[1,0]
	v_mul_f32_e32 v153, v153, v190
	v_sub_f32_e32 v64, v64, v189
	v_sub_f32_e32 v65, v65, v189
	v_sub_f32_e32 v66, v66, v189
	v_sub_f32_e32 v67, v67, v189
	v_sub_f32_e32 v68, v68, v189
	v_sub_f32_e32 v69, v69, v189
	v_sub_f32_e32 v70, v70, v189
	v_sub_f32_e32 v71, v71, v189
	v_sub_f32_e32 v72, v72, v189
	v_sub_f32_e32 v73, v73, v189
	v_sub_f32_e32 v74, v74, v189
	v_sub_f32_e32 v75, v75, v189
	v_sub_f32_e32 v76, v76, v189
	v_sub_f32_e32 v77, v77, v189
	v_sub_f32_e32 v78, v78, v189
	v_sub_f32_e32 v79, v79, v189
	v_sub_f32_e32 v80, v80, v189
	v_sub_f32_e32 v81, v81, v189
	v_sub_f32_e32 v82, v82, v189
	v_sub_f32_e32 v83, v83, v189
	v_sub_f32_e32 v84, v84, v189
	v_sub_f32_e32 v85, v85, v189
	v_sub_f32_e32 v86, v86, v189
	v_sub_f32_e32 v87, v87, v189
	v_sub_f32_e32 v88, v88, v189
	v_sub_f32_e32 v89, v89, v189
	v_sub_f32_e32 v90, v90, v189
	v_sub_f32_e32 v91, v91, v189
	v_sub_f32_e32 v92, v92, v189
	v_sub_f32_e32 v93, v93, v189
	v_sub_f32_e32 v94, v94, v189
	v_sub_f32_e32 v95, v95, v189
	v_sub_f32_e32 v238, v238, v189
	v_sub_f32_e32 v239, v239, v189
	v_sub_f32_e32 v240, v240, v189
	v_sub_f32_e32 v241, v241, v189
	v_sub_f32_e32 v242, v242, v189
	v_sub_f32_e32 v243, v243, v189
	v_sub_f32_e32 v244, v244, v189
	v_sub_f32_e32 v245, v245, v189
	v_sub_f32_e32 v246, v246, v189
	v_sub_f32_e32 v247, v247, v189
	v_sub_f32_e32 v248, v248, v189
	v_sub_f32_e32 v249, v249, v189
	v_sub_f32_e32 v250, v250, v189
	v_sub_f32_e32 v251, v251, v189
	v_sub_f32_e32 v252, v252, v189
	v_sub_f32_e32 v253, v253, v189
